# phase 4 groupnorm statistics loop software-pipelined (next row loads issued before the current row is reduced)
# baseline (speedup 1.0000x reference)
.LBB0_443:
	s_or_b64 exec, exec, s[0:1]
	s_waitcnt lgkmcnt(0)
	v_cndmask_b32_e64 v0, 0, 1, s[6:7]
	v_cmp_ne_u32_e64 s[54:55], 1, v0
	s_andn2_b64 vcc, exec, s[6:7]
	s_barrier
	s_cbranch_vccnz .LBB0_448
	s_waitcnt vmcnt(48)
	v_mbcnt_hi_u32_b32 v4, -1, v221
	s_add_u32 s0, s72, 0x7100000
	v_and_b32_e32 v0, 64, v4
	s_addc_u32 s1, s73, 0
	s_lshl_b32 s3, s2, 2
	s_lshl_b32 s4, s74, 2
	v_mov_b32_e32 v1, 0
	v_add_u32_e32 v5, 64, v0
	v_xor_b32_e32 v6, 8, v4
	v_xor_b32_e32 v7, 4, v4
	v_xor_b32_e32 v8, 2, v4
	v_xor_b32_e32 v9, 1, v4
	v_mov_b32_e32 v10, 0x358637bd
	s_mov_b32 s5, 0x800000
	s_mov_b32 s8, s2
	s_waitcnt vmcnt(0)
	v_ashrrev_i32_e32 v69, 6, v220
	v_and_b32_e32 v11, 63, v220
	v_lshlrev_b32_e32 v72, 6, v11
	v_mov_b32_e32 v73, 0
	v_lshrrev_b32_e32 v50, 1, v11
	v_mov_b32_e32 v51, 0
	v_and_b32_e32 v14, 15, v220
	v_cmp_eq_u32_e64 s[52:53], 0, v14
	v_cmp_lt_i32_e32 vcc, v6, v5
	v_cndmask_b32_e32 v28, v4, v6, vcc
	v_lshlrev_b32_e32 v28, 2, v28
	v_cmp_lt_i32_e32 vcc, v7, v5
	v_cndmask_b32_e32 v47, v4, v7, vcc
	v_lshlrev_b32_e32 v47, 2, v47
	v_cmp_lt_i32_e32 vcc, v8, v5
	v_cndmask_b32_e32 v48, v4, v8, vcc
	v_lshlrev_b32_e32 v48, 2, v48
	v_cmp_lt_i32_e32 vcc, v9, v5
	v_cndmask_b32_e32 v49, v4, v9, vcc
	v_lshlrev_b32_e32 v49, 2, v49
	v_add_u32_e32 v74, s3, v69
	v_ashrrev_i32_e32 v75, 31, v74
	v_lshlrev_b64 v[12:13], 12, v[74:75]
	v_lshl_add_u64 v[12:13], s[70:71], 0, v[12:13]
	v_lshl_add_u64 v[70:71], v[12:13], 0, v[72:73]
	global_load_dwordx4 v[12:15], v[70:71], off
	global_load_dwordx4 v[16:19], v[70:71], off offset:16
	global_load_dwordx4 v[20:23], v[70:71], off offset:32
	global_load_dwordx4 v[24:27], v[70:71], off offset:48
	s_add_i32 s9, s3, s4
	s_min_i32 s9, s9, 0x7ffc
	v_add_u32_e32 v76, s9, v69
	v_ashrrev_i32_e32 v77, 31, v76
	v_lshlrev_b64 v[52:53], 12, v[76:77]
	v_lshl_add_u64 v[52:53], s[70:71], 0, v[52:53]
	v_lshl_add_u64 v[70:71], v[52:53], 0, v[72:73]
	global_load_dwordx4 v[52:55], v[70:71], off
	global_load_dwordx4 v[56:59], v[70:71], off offset:16
	global_load_dwordx4 v[60:63], v[70:71], off offset:32
	global_load_dwordx4 v[64:67], v[70:71], off offset:48
	s_waitcnt vmcnt(7)
	v_lshlrev_b32_e32 v29, 16, v12
	v_and_b32_e32 v12, 0xffff0000, v12
	v_add_f32_e32 v0, 0, v29
	v_add_f32_e32 v0, v0, v12
	v_lshlrev_b32_e32 v31, 16, v13
	v_add_f32_e32 v0, v0, v31
	v_and_b32_e32 v13, 0xffff0000, v13
	v_add_f32_e32 v0, v0, v13
	v_lshlrev_b32_e32 v32, 16, v14
	v_add_f32_e32 v0, v0, v32
	v_and_b32_e32 v14, 0xffff0000, v14
	v_add_f32_e32 v0, v0, v14
	v_lshlrev_b32_e32 v33, 16, v15
	v_add_f32_e32 v0, v0, v33
	v_and_b32_e32 v15, 0xffff0000, v15
	v_add_f32_e32 v0, v0, v15
	s_waitcnt vmcnt(6)
	v_lshlrev_b32_e32 v34, 16, v16
	v_add_f32_e32 v0, v0, v34
	v_and_b32_e32 v16, 0xffff0000, v16
	v_add_f32_e32 v0, v0, v16
	v_lshlrev_b32_e32 v35, 16, v17
	v_add_f32_e32 v0, v0, v35
	v_and_b32_e32 v17, 0xffff0000, v17
	v_add_f32_e32 v0, v0, v17
	v_lshlrev_b32_e32 v36, 16, v18
	v_add_f32_e32 v0, v0, v36
	v_and_b32_e32 v18, 0xffff0000, v18
	v_add_f32_e32 v0, v0, v18
	v_lshlrev_b32_e32 v37, 16, v19
	v_add_f32_e32 v0, v0, v37
	v_and_b32_e32 v19, 0xffff0000, v19
	v_add_f32_e32 v0, v0, v19
	s_waitcnt vmcnt(5)
	v_lshlrev_b32_e32 v38, 16, v20
	v_add_f32_e32 v0, v0, v38
	v_and_b32_e32 v20, 0xffff0000, v20
	v_add_f32_e32 v0, v0, v20
	v_lshlrev_b32_e32 v39, 16, v21
	v_add_f32_e32 v0, v0, v39
	v_and_b32_e32 v21, 0xffff0000, v21
	v_add_f32_e32 v0, v0, v21
	v_lshlrev_b32_e32 v40, 16, v22
	v_add_f32_e32 v0, v0, v40
	v_and_b32_e32 v22, 0xffff0000, v22
	v_add_f32_e32 v0, v0, v22
	v_lshlrev_b32_e32 v41, 16, v23
	v_add_f32_e32 v0, v0, v41
	v_and_b32_e32 v23, 0xffff0000, v23
	v_add_f32_e32 v0, v0, v23
	s_waitcnt vmcnt(4)
	v_lshlrev_b32_e32 v42, 16, v24
	v_add_f32_e32 v0, v0, v42
	v_and_b32_e32 v24, 0xffff0000, v24
	v_add_f32_e32 v0, v0, v24
	v_lshlrev_b32_e32 v43, 16, v25
	v_add_f32_e32 v0, v0, v43
	v_and_b32_e32 v25, 0xffff0000, v25
	v_add_f32_e32 v0, v0, v25
	v_lshlrev_b32_e32 v44, 16, v26
	v_add_f32_e32 v0, v0, v44
	v_and_b32_e32 v26, 0xffff0000, v26
	v_add_f32_e32 v0, v0, v26
	v_lshlrev_b32_e32 v45, 16, v27
	v_add_f32_e32 v0, v0, v45
	v_and_b32_e32 v27, 0xffff0000, v27
	v_add_f32_e32 v0, v0, v27
	ds_bpermute_b32 v46, v28, v0
	s_waitcnt lgkmcnt(0)
	v_add_f32_e32 v0, v0, v46
	ds_bpermute_b32 v46, v47, v0
	s_waitcnt lgkmcnt(0)
	v_add_f32_e32 v0, v0, v46
	ds_bpermute_b32 v46, v48, v0
	s_waitcnt lgkmcnt(0)
	v_add_f32_e32 v0, v0, v46
	ds_bpermute_b32 v46, v49, v0
	s_waitcnt lgkmcnt(0)
	v_add_f32_e32 v0, v0, v46
	v_fmac_f32_e32 v12, 0xbb000000, v0
	v_fmac_f32_e32 v29, 0xbb000000, v0
	v_mul_f32_e32 v12, v12, v12
	v_fmac_f32_e32 v12, v29, v29
	v_fmac_f32_e32 v31, 0xbb000000, v0
	v_fmac_f32_e32 v12, v31, v31
	v_fmac_f32_e32 v13, 0xbb000000, v0
	v_fmac_f32_e32 v12, v13, v13
	v_fmac_f32_e32 v32, 0xbb000000, v0
	v_fmac_f32_e32 v12, v32, v32
	v_fmac_f32_e32 v14, 0xbb000000, v0
	v_fmac_f32_e32 v12, v14, v14
	v_fmac_f32_e32 v33, 0xbb000000, v0
	v_fmac_f32_e32 v12, v33, v33
	v_fmac_f32_e32 v15, 0xbb000000, v0
	v_fmac_f32_e32 v12, v15, v15
	v_fmac_f32_e32 v34, 0xbb000000, v0
	v_fmac_f32_e32 v12, v34, v34
	v_fmac_f32_e32 v16, 0xbb000000, v0
	v_fmac_f32_e32 v12, v16, v16
	v_fmac_f32_e32 v35, 0xbb000000, v0
	v_fmac_f32_e32 v12, v35, v35
	v_fmac_f32_e32 v17, 0xbb000000, v0
	v_fmac_f32_e32 v12, v17, v17
	v_fmac_f32_e32 v36, 0xbb000000, v0
	v_fmac_f32_e32 v12, v36, v36
	v_fmac_f32_e32 v18, 0xbb000000, v0
	v_fmac_f32_e32 v12, v18, v18
	v_fmac_f32_e32 v37, 0xbb000000, v0
	v_fmac_f32_e32 v12, v37, v37
	v_fmac_f32_e32 v19, 0xbb000000, v0
	v_fmac_f32_e32 v12, v19, v19
	v_fmac_f32_e32 v38, 0xbb000000, v0
	v_fmac_f32_e32 v12, v38, v38
	v_fmac_f32_e32 v20, 0xbb000000, v0
	v_fmac_f32_e32 v12, v20, v20
	v_fmac_f32_e32 v39, 0xbb000000, v0
	v_fmac_f32_e32 v12, v39, v39
	v_fmac_f32_e32 v21, 0xbb000000, v0
	v_fmac_f32_e32 v12, v21, v21
	v_fmac_f32_e32 v40, 0xbb000000, v0
	v_fmac_f32_e32 v12, v40, v40
	v_fmac_f32_e32 v22, 0xbb000000, v0
	v_fmac_f32_e32 v12, v22, v22
	v_fmac_f32_e32 v41, 0xbb000000, v0
	v_fmac_f32_e32 v12, v41, v41
	v_fmac_f32_e32 v23, 0xbb000000, v0
	v_fmac_f32_e32 v12, v23, v23
	v_fmac_f32_e32 v42, 0xbb000000, v0
	v_fmac_f32_e32 v12, v42, v42
	v_fmac_f32_e32 v24, 0xbb000000, v0
	v_fmac_f32_e32 v12, v24, v24
	v_fmac_f32_e32 v43, 0xbb000000, v0
	v_fmac_f32_e32 v12, v43, v43
	v_fmac_f32_e32 v25, 0xbb000000, v0
	v_fmac_f32_e32 v12, v25, v25
	v_fmac_f32_e32 v44, 0xbb000000, v0
	v_fmac_f32_e32 v12, v44, v44
	v_fmac_f32_e32 v26, 0xbb000000, v0
	v_fmac_f32_e32 v12, v26, v26
	v_fmac_f32_e32 v45, 0xbb000000, v0
	v_fmac_f32_e32 v12, v45, v45
	v_fmac_f32_e32 v27, 0xbb000000, v0
	v_fmac_f32_e32 v12, v27, v27
	ds_bpermute_b32 v13, v28, v12
	s_waitcnt lgkmcnt(0)
	v_add_f32_e32 v12, v12, v13
	ds_bpermute_b32 v13, v47, v12
	s_waitcnt lgkmcnt(0)
	v_add_f32_e32 v12, v12, v13
	ds_bpermute_b32 v13, v48, v12
	s_waitcnt lgkmcnt(0)
	v_add_f32_e32 v12, v12, v13
	ds_bpermute_b32 v13, v49, v12
	s_and_saveexec_b64 s[6:7], s[52:53]
	v_mul_f32_e32 v14, 0x3b000000, v0
	s_waitcnt lgkmcnt(0)
	v_add_f32_e32 v0, v12, v13
	v_fmamk_f32 v0, v0, 0x3b000000, v10
	v_mul_f32_e32 v12, 0x4b800000, v0
	v_cmp_gt_f32_e32 vcc, s5, v0
	v_lshlrev_b64 v[2:3], 5, v[74:75]
	v_lshl_add_u64 v[2:3], s[0:1], 0, v[2:3]
	v_cndmask_b32_e32 v0, v0, v12, vcc
	v_rsq_f32_e32 v12, v0
	v_lshl_add_u64 v[2:3], v[2:3], 0, v[50:51]
	v_mul_f32_e32 v0, 0x45800000, v12
	v_cndmask_b32_e32 v15, v12, v0, vcc
	global_store_dwordx2 v[2:3], v[14:15], off
	s_or_b64 exec, exec, s[6:7]
	s_add_i32 s8, s8, s74
	s_add_i32 s3, s3, s4
	s_cmpk_lt_i32 s8, 0x2000
	s_cbranch_scc0 .LBB0_448
.Lst_loop:
	s_add_i32 s9, s3, s4
	s_min_i32 s9, s9, 0x7ffc
	v_add_u32_e32 v74, s9, v69
	v_ashrrev_i32_e32 v75, 31, v74
	v_lshlrev_b64 v[12:13], 12, v[74:75]
	v_lshl_add_u64 v[12:13], s[70:71], 0, v[12:13]
	v_lshl_add_u64 v[70:71], v[12:13], 0, v[72:73]
	global_load_dwordx4 v[12:15], v[70:71], off
	global_load_dwordx4 v[16:19], v[70:71], off offset:16
	global_load_dwordx4 v[20:23], v[70:71], off offset:32
	global_load_dwordx4 v[24:27], v[70:71], off offset:48
	s_waitcnt vmcnt(8)
	v_lshlrev_b32_e32 v29, 16, v52
	v_and_b32_e32 v52, 0xffff0000, v52
	v_add_f32_e32 v0, 0, v29
	v_add_f32_e32 v0, v0, v52
	v_lshlrev_b32_e32 v31, 16, v53
	v_add_f32_e32 v0, v0, v31
	v_and_b32_e32 v53, 0xffff0000, v53
	v_add_f32_e32 v0, v0, v53
	v_lshlrev_b32_e32 v32, 16, v54
	v_add_f32_e32 v0, v0, v32
	v_and_b32_e32 v54, 0xffff0000, v54
	v_add_f32_e32 v0, v0, v54
	v_lshlrev_b32_e32 v33, 16, v55
	v_add_f32_e32 v0, v0, v33
	v_and_b32_e32 v55, 0xffff0000, v55
	v_add_f32_e32 v0, v0, v55
	s_waitcnt vmcnt(7)
	v_lshlrev_b32_e32 v34, 16, v56
	v_add_f32_e32 v0, v0, v34
	v_and_b32_e32 v56, 0xffff0000, v56
	v_add_f32_e32 v0, v0, v56
	v_lshlrev_b32_e32 v35, 16, v57
	v_add_f32_e32 v0, v0, v35
	v_and_b32_e32 v57, 0xffff0000, v57
	v_add_f32_e32 v0, v0, v57
	v_lshlrev_b32_e32 v36, 16, v58
	v_add_f32_e32 v0, v0, v36
	v_and_b32_e32 v58, 0xffff0000, v58
	v_add_f32_e32 v0, v0, v58
	v_lshlrev_b32_e32 v37, 16, v59
	v_add_f32_e32 v0, v0, v37
	v_and_b32_e32 v59, 0xffff0000, v59
	v_add_f32_e32 v0, v0, v59
	s_waitcnt vmcnt(6)
	v_lshlrev_b32_e32 v38, 16, v60
	v_add_f32_e32 v0, v0, v38
	v_and_b32_e32 v60, 0xffff0000, v60
	v_add_f32_e32 v0, v0, v60
	v_lshlrev_b32_e32 v39, 16, v61
	v_add_f32_e32 v0, v0, v39
	v_and_b32_e32 v61, 0xffff0000, v61
	v_add_f32_e32 v0, v0, v61
	v_lshlrev_b32_e32 v40, 16, v62
	v_add_f32_e32 v0, v0, v40
	v_and_b32_e32 v62, 0xffff0000, v62
	v_add_f32_e32 v0, v0, v62
	v_lshlrev_b32_e32 v41, 16, v63
	v_add_f32_e32 v0, v0, v41
	v_and_b32_e32 v63, 0xffff0000, v63
	v_add_f32_e32 v0, v0, v63
	s_waitcnt vmcnt(5)
	v_lshlrev_b32_e32 v42, 16, v64
	v_add_f32_e32 v0, v0, v42
	v_and_b32_e32 v64, 0xffff0000, v64
	v_add_f32_e32 v0, v0, v64
	v_lshlrev_b32_e32 v43, 16, v65
	v_add_f32_e32 v0, v0, v43
	v_and_b32_e32 v65, 0xffff0000, v65
	v_add_f32_e32 v0, v0, v65
	v_lshlrev_b32_e32 v44, 16, v66
	v_add_f32_e32 v0, v0, v44
	v_and_b32_e32 v66, 0xffff0000, v66
	v_add_f32_e32 v0, v0, v66
	v_lshlrev_b32_e32 v45, 16, v67
	v_add_f32_e32 v0, v0, v45
	v_and_b32_e32 v67, 0xffff0000, v67
	v_add_f32_e32 v0, v0, v67
	ds_bpermute_b32 v46, v28, v0
	s_waitcnt lgkmcnt(0)
	v_add_f32_e32 v0, v0, v46
	ds_bpermute_b32 v46, v47, v0
	s_waitcnt lgkmcnt(0)
	v_add_f32_e32 v0, v0, v46
	ds_bpermute_b32 v46, v48, v0
	s_waitcnt lgkmcnt(0)
	v_add_f32_e32 v0, v0, v46
	ds_bpermute_b32 v46, v49, v0
	s_waitcnt lgkmcnt(0)
	v_add_f32_e32 v0, v0, v46
	v_fmac_f32_e32 v52, 0xbb000000, v0
	v_fmac_f32_e32 v29, 0xbb000000, v0
	v_mul_f32_e32 v52, v52, v52
	v_fmac_f32_e32 v52, v29, v29
	v_fmac_f32_e32 v31, 0xbb000000, v0
	v_fmac_f32_e32 v52, v31, v31
	v_fmac_f32_e32 v53, 0xbb000000, v0
	v_fmac_f32_e32 v52, v53, v53
	v_fmac_f32_e32 v32, 0xbb000000, v0
	v_fmac_f32_e32 v52, v32, v32
	v_fmac_f32_e32 v54, 0xbb000000, v0
	v_fmac_f32_e32 v52, v54, v54
	v_fmac_f32_e32 v33, 0xbb000000, v0
	v_fmac_f32_e32 v52, v33, v33
	v_fmac_f32_e32 v55, 0xbb000000, v0
	v_fmac_f32_e32 v52, v55, v55
	v_fmac_f32_e32 v34, 0xbb000000, v0
	v_fmac_f32_e32 v52, v34, v34
	v_fmac_f32_e32 v56, 0xbb000000, v0
	v_fmac_f32_e32 v52, v56, v56
	v_fmac_f32_e32 v35, 0xbb000000, v0
	v_fmac_f32_e32 v52, v35, v35
	v_fmac_f32_e32 v57, 0xbb000000, v0
	v_fmac_f32_e32 v52, v57, v57
	v_fmac_f32_e32 v36, 0xbb000000, v0
	v_fmac_f32_e32 v52, v36, v36
	v_fmac_f32_e32 v58, 0xbb000000, v0
	v_fmac_f32_e32 v52, v58, v58
	v_fmac_f32_e32 v37, 0xbb000000, v0
	v_fmac_f32_e32 v52, v37, v37
	v_fmac_f32_e32 v59, 0xbb000000, v0
	v_fmac_f32_e32 v52, v59, v59
	v_fmac_f32_e32 v38, 0xbb000000, v0
	v_fmac_f32_e32 v52, v38, v38
	v_fmac_f32_e32 v60, 0xbb000000, v0
	v_fmac_f32_e32 v52, v60, v60
	v_fmac_f32_e32 v39, 0xbb000000, v0
	v_fmac_f32_e32 v52, v39, v39
	v_fmac_f32_e32 v61, 0xbb000000, v0
	v_fmac_f32_e32 v52, v61, v61
	v_fmac_f32_e32 v40, 0xbb000000, v0
	v_fmac_f32_e32 v52, v40, v40
	v_fmac_f32_e32 v62, 0xbb000000, v0
	v_fmac_f32_e32 v52, v62, v62
	v_fmac_f32_e32 v41, 0xbb000000, v0
	v_fmac_f32_e32 v52, v41, v41
	v_fmac_f32_e32 v63, 0xbb000000, v0
	v_fmac_f32_e32 v52, v63, v63
	v_fmac_f32_e32 v42, 0xbb000000, v0
	v_fmac_f32_e32 v52, v42, v42
	v_fmac_f32_e32 v64, 0xbb000000, v0
	v_fmac_f32_e32 v52, v64, v64
	v_fmac_f32_e32 v43, 0xbb000000, v0
	v_fmac_f32_e32 v52, v43, v43
	v_fmac_f32_e32 v65, 0xbb000000, v0
	v_fmac_f32_e32 v52, v65, v65
	v_fmac_f32_e32 v44, 0xbb000000, v0
	v_fmac_f32_e32 v52, v44, v44
	v_fmac_f32_e32 v66, 0xbb000000, v0
	v_fmac_f32_e32 v52, v66, v66
	v_fmac_f32_e32 v45, 0xbb000000, v0
	v_fmac_f32_e32 v52, v45, v45
	v_fmac_f32_e32 v67, 0xbb000000, v0
	v_fmac_f32_e32 v52, v67, v67
	ds_bpermute_b32 v53, v28, v52
	s_waitcnt lgkmcnt(0)
	v_add_f32_e32 v52, v52, v53
	ds_bpermute_b32 v53, v47, v52
	s_waitcnt lgkmcnt(0)
	v_add_f32_e32 v52, v52, v53
	ds_bpermute_b32 v53, v48, v52
	s_waitcnt lgkmcnt(0)
	v_add_f32_e32 v52, v52, v53
	ds_bpermute_b32 v53, v49, v52
	s_and_saveexec_b64 s[6:7], s[52:53]
	v_mul_f32_e32 v54, 0x3b000000, v0
	s_waitcnt lgkmcnt(0)
	v_add_f32_e32 v0, v52, v53
	v_fmamk_f32 v0, v0, 0x3b000000, v10
	v_mul_f32_e32 v52, 0x4b800000, v0
	v_cmp_gt_f32_e32 vcc, s5, v0
	v_lshlrev_b64 v[2:3], 5, v[76:77]
	v_lshl_add_u64 v[2:3], s[0:1], 0, v[2:3]
	v_cndmask_b32_e32 v0, v0, v52, vcc
	v_rsq_f32_e32 v52, v0
	v_lshl_add_u64 v[2:3], v[2:3], 0, v[50:51]
	v_mul_f32_e32 v0, 0x45800000, v52
	v_cndmask_b32_e32 v55, v52, v0, vcc
	global_store_dwordx2 v[2:3], v[54:55], off
	s_or_b64 exec, exec, s[6:7]
	s_add_i32 s8, s8, s74
	s_add_i32 s3, s3, s4
	s_cmpk_lt_i32 s8, 0x2000
	s_cbranch_scc0 .LBB0_448
	s_add_i32 s9, s3, s4
	s_min_i32 s9, s9, 0x7ffc
	v_add_u32_e32 v76, s9, v69
	v_ashrrev_i32_e32 v77, 31, v76
	v_lshlrev_b64 v[52:53], 12, v[76:77]
	v_lshl_add_u64 v[52:53], s[70:71], 0, v[52:53]
	v_lshl_add_u64 v[70:71], v[52:53], 0, v[72:73]
	global_load_dwordx4 v[52:55], v[70:71], off
	global_load_dwordx4 v[56:59], v[70:71], off offset:16
	global_load_dwordx4 v[60:63], v[70:71], off offset:32
	global_load_dwordx4 v[64:67], v[70:71], off offset:48
	s_waitcnt vmcnt(8)
	v_lshlrev_b32_e32 v29, 16, v12
	v_and_b32_e32 v12, 0xffff0000, v12
	v_add_f32_e32 v0, 0, v29
	v_add_f32_e32 v0, v0, v12
	v_lshlrev_b32_e32 v31, 16, v13
	v_add_f32_e32 v0, v0, v31
	v_and_b32_e32 v13, 0xffff0000, v13
	v_add_f32_e32 v0, v0, v13
	v_lshlrev_b32_e32 v32, 16, v14
	v_add_f32_e32 v0, v0, v32
	v_and_b32_e32 v14, 0xffff0000, v14
	v_add_f32_e32 v0, v0, v14
	v_lshlrev_b32_e32 v33, 16, v15
	v_add_f32_e32 v0, v0, v33
	v_and_b32_e32 v15, 0xffff0000, v15
	v_add_f32_e32 v0, v0, v15
	s_waitcnt vmcnt(7)
	v_lshlrev_b32_e32 v34, 16, v16
	v_add_f32_e32 v0, v0, v34
	v_and_b32_e32 v16, 0xffff0000, v16
	v_add_f32_e32 v0, v0, v16
	v_lshlrev_b32_e32 v35, 16, v17
	v_add_f32_e32 v0, v0, v35
	v_and_b32_e32 v17, 0xffff0000, v17
	v_add_f32_e32 v0, v0, v17
	v_lshlrev_b32_e32 v36, 16, v18
	v_add_f32_e32 v0, v0, v36
	v_and_b32_e32 v18, 0xffff0000, v18
	v_add_f32_e32 v0, v0, v18
	v_lshlrev_b32_e32 v37, 16, v19
	v_add_f32_e32 v0, v0, v37
	v_and_b32_e32 v19, 0xffff0000, v19
	v_add_f32_e32 v0, v0, v19
	s_waitcnt vmcnt(6)
	v_lshlrev_b32_e32 v38, 16, v20
	v_add_f32_e32 v0, v0, v38
	v_and_b32_e32 v20, 0xffff0000, v20
	v_add_f32_e32 v0, v0, v20
	v_lshlrev_b32_e32 v39, 16, v21
	v_add_f32_e32 v0, v0, v39
	v_and_b32_e32 v21, 0xffff0000, v21
	v_add_f32_e32 v0, v0, v21
	v_lshlrev_b32_e32 v40, 16, v22
	v_add_f32_e32 v0, v0, v40
	v_and_b32_e32 v22, 0xffff0000, v22
	v_add_f32_e32 v0, v0, v22
	v_lshlrev_b32_e32 v41, 16, v23
	v_add_f32_e32 v0, v0, v41
	v_and_b32_e32 v23, 0xffff0000, v23
	v_add_f32_e32 v0, v0, v23
	s_waitcnt vmcnt(5)
	v_lshlrev_b32_e32 v42, 16, v24
	v_add_f32_e32 v0, v0, v42
	v_and_b32_e32 v24, 0xffff0000, v24
	v_add_f32_e32 v0, v0, v24
	v_lshlrev_b32_e32 v43, 16, v25
	v_add_f32_e32 v0, v0, v43
	v_and_b32_e32 v25, 0xffff0000, v25
	v_add_f32_e32 v0, v0, v25
	v_lshlrev_b32_e32 v44, 16, v26
	v_add_f32_e32 v0, v0, v44
	v_and_b32_e32 v26, 0xffff0000, v26
	v_add_f32_e32 v0, v0, v26
	v_lshlrev_b32_e32 v45, 16, v27
	v_add_f32_e32 v0, v0, v45
	v_and_b32_e32 v27, 0xffff0000, v27
	v_add_f32_e32 v0, v0, v27
	ds_bpermute_b32 v46, v28, v0
	s_waitcnt lgkmcnt(0)
	v_add_f32_e32 v0, v0, v46
	ds_bpermute_b32 v46, v47, v0
	s_waitcnt lgkmcnt(0)
	v_add_f32_e32 v0, v0, v46
	ds_bpermute_b32 v46, v48, v0
	s_waitcnt lgkmcnt(0)
	v_add_f32_e32 v0, v0, v46
	ds_bpermute_b32 v46, v49, v0
	s_waitcnt lgkmcnt(0)
	v_add_f32_e32 v0, v0, v46
	v_fmac_f32_e32 v12, 0xbb000000, v0
	v_fmac_f32_e32 v29, 0xbb000000, v0
	v_mul_f32_e32 v12, v12, v12
	v_fmac_f32_e32 v12, v29, v29
	v_fmac_f32_e32 v31, 0xbb000000, v0
	v_fmac_f32_e32 v12, v31, v31
	v_fmac_f32_e32 v13, 0xbb000000, v0
	v_fmac_f32_e32 v12, v13, v13
	v_fmac_f32_e32 v32, 0xbb000000, v0
	v_fmac_f32_e32 v12, v32, v32
	v_fmac_f32_e32 v14, 0xbb000000, v0
	v_fmac_f32_e32 v12, v14, v14
	v_fmac_f32_e32 v33, 0xbb000000, v0
	v_fmac_f32_e32 v12, v33, v33
	v_fmac_f32_e32 v15, 0xbb000000, v0
	v_fmac_f32_e32 v12, v15, v15
	v_fmac_f32_e32 v34, 0xbb000000, v0
	v_fmac_f32_e32 v12, v34, v34
	v_fmac_f32_e32 v16, 0xbb000000, v0
	v_fmac_f32_e32 v12, v16, v16
	v_fmac_f32_e32 v35, 0xbb000000, v0
	v_fmac_f32_e32 v12, v35, v35
	v_fmac_f32_e32 v17, 0xbb000000, v0
	v_fmac_f32_e32 v12, v17, v17
	v_fmac_f32_e32 v36, 0xbb000000, v0
	v_fmac_f32_e32 v12, v36, v36
	v_fmac_f32_e32 v18, 0xbb000000, v0
	v_fmac_f32_e32 v12, v18, v18
	v_fmac_f32_e32 v37, 0xbb000000, v0
	v_fmac_f32_e32 v12, v37, v37
	v_fmac_f32_e32 v19, 0xbb000000, v0
	v_fmac_f32_e32 v12, v19, v19
	v_fmac_f32_e32 v38, 0xbb000000, v0
	v_fmac_f32_e32 v12, v38, v38
	v_fmac_f32_e32 v20, 0xbb000000, v0
	v_fmac_f32_e32 v12, v20, v20
	v_fmac_f32_e32 v39, 0xbb000000, v0
	v_fmac_f32_e32 v12, v39, v39
	v_fmac_f32_e32 v21, 0xbb000000, v0
	v_fmac_f32_e32 v12, v21, v21
	v_fmac_f32_e32 v40, 0xbb000000, v0
	v_fmac_f32_e32 v12, v40, v40
	v_fmac_f32_e32 v22, 0xbb000000, v0
	v_fmac_f32_e32 v12, v22, v22
	v_fmac_f32_e32 v41, 0xbb000000, v0
	v_fmac_f32_e32 v12, v41, v41
	v_fmac_f32_e32 v23, 0xbb000000, v0
	v_fmac_f32_e32 v12, v23, v23
	v_fmac_f32_e32 v42, 0xbb000000, v0
	v_fmac_f32_e32 v12, v42, v42
	v_fmac_f32_e32 v24, 0xbb000000, v0
	v_fmac_f32_e32 v12, v24, v24
	v_fmac_f32_e32 v43, 0xbb000000, v0
	v_fmac_f32_e32 v12, v43, v43
	v_fmac_f32_e32 v25, 0xbb000000, v0
	v_fmac_f32_e32 v12, v25, v25
	v_fmac_f32_e32 v44, 0xbb000000, v0
	v_fmac_f32_e32 v12, v44, v44
	v_fmac_f32_e32 v26, 0xbb000000, v0
	v_fmac_f32_e32 v12, v26, v26
	v_fmac_f32_e32 v45, 0xbb000000, v0
	v_fmac_f32_e32 v12, v45, v45
	v_fmac_f32_e32 v27, 0xbb000000, v0
	v_fmac_f32_e32 v12, v27, v27
	ds_bpermute_b32 v13, v28, v12
	s_waitcnt lgkmcnt(0)
	v_add_f32_e32 v12, v12, v13
	ds_bpermute_b32 v13, v47, v12
	s_waitcnt lgkmcnt(0)
	v_add_f32_e32 v12, v12, v13
	ds_bpermute_b32 v13, v48, v12
	s_waitcnt lgkmcnt(0)
	v_add_f32_e32 v12, v12, v13
	ds_bpermute_b32 v13, v49, v12
	s_and_saveexec_b64 s[6:7], s[52:53]
	v_mul_f32_e32 v14, 0x3b000000, v0
	s_waitcnt lgkmcnt(0)
	v_add_f32_e32 v0, v12, v13
	v_fmamk_f32 v0, v0, 0x3b000000, v10
	v_mul_f32_e32 v12, 0x4b800000, v0
	v_cmp_gt_f32_e32 vcc, s5, v0
	v_lshlrev_b64 v[2:3], 5, v[74:75]
	v_lshl_add_u64 v[2:3], s[0:1], 0, v[2:3]
	v_cndmask_b32_e32 v0, v0, v12, vcc
	v_rsq_f32_e32 v12, v0
	v_lshl_add_u64 v[2:3], v[2:3], 0, v[50:51]
	v_mul_f32_e32 v0, 0x45800000, v12
	v_cndmask_b32_e32 v15, v12, v0, vcc
	global_store_dwordx2 v[2:3], v[14:15], off
	s_or_b64 exec, exec, s[6:7]
	s_add_i32 s8, s8, s74
	s_add_i32 s3, s3, s4
	s_cmpk_lt_i32 s8, 0x2000
	s_cbranch_scc1 .Lst_loop
